# grid barriers: the per-workgroup L2 writeback (buffer_wbl2) is dropped; the last arriver of each XCD group still writes that XCD's L2 back before the top-level arrive (groups are blockIdx & 7 = XCD un
# speedup vs baseline: 1.0656x; 1.0656x over previous
; DI void grid_barrier(const Ctx& c, unsigned idx) {
;     ...
;   asm volatile("s_waitcnt vmcnt(0)" ::: "memory");
;   __syncthreads();
;   if (TIDX == 0) {
;     unsigned* bar = (unsigned*)(p.ws + OFF_BAR);
;     const unsigned G = gridDim.x, grp = blockIdx.x & 7u;
;     const unsigned gsz = (G >> 3) + ((grp < (G & 7u)) ? 1u : 0u);
;     const unsigned ngrp = G < 8u ? G : 8u;
;     __builtin_amdgcn_fence(__ATOMIC_RELEASE, "agent");
;     asm volatile("s_waitcnt vmcnt(0)" ::: "memory");
;     const unsigned old = __hip_atomic_fetch_add(bar + 64 * (1 + grp), 1u, __ATOMIC_RELAXED, __HIP_MEMORY_SCOPE_AGENT);
.LBB0_330:
	s_cmp_lt_i32 s95, 3
	s_cbranch_scc1 .LBB0_344
	s_waitcnt vmcnt(0)
	v_sub_u32_e32 v0, 0, v195
	v_cmp_eq_u32_e32 vcc, s28, v0
	s_barrier
	s_and_saveexec_b64 s[0:1], vcc
	s_cbranch_execz .LBB0_343
	s_add_u32 s6, s92, 0x1fe00000
	s_mov_b64 s[4:5], exec
	s_addc_u32 s7, s93, 0
	s_and_b32 s10, s96, 7
	s_nop 0
	s_waitcnt vmcnt(0)
	s_waitcnt vmcnt(0)
	s_lshl_b32 s2, s10, 8
	v_mbcnt_lo_u32_b32 v0, s4, 0
	s_add_u32 s2, s6, s2
	v_mbcnt_hi_u32_b32 v0, s5, v0
	s_addc_u32 s3, s7, 0
	v_cmp_eq_u32_e32 vcc, 0, v0
	s_and_saveexec_b64 s[8:9], vcc
	s_cbranch_execz .LBB0_334
	s_bcnt1_i32_b64 s4, s[4:5]
	v_mov_b32_e32 v1, 0
	v_mov_b32_e32 v2, s4
	global_atomic_add v1, v1, v2, s[2:3] offset:256 sc0

; DI void grid_barrier(const Ctx& c, unsigned idx) {
;     ...
;   asm volatile("s_waitcnt vmcnt(0)" ::: "memory");
;   __syncthreads();
;   if (TIDX == 0) {
;     unsigned* bar = (unsigned*)(p.ws + OFF_BAR);
;     const unsigned G = gridDim.x, grp = blockIdx.x & 7u;
;     const unsigned gsz = (G >> 3) + ((grp < (G & 7u)) ? 1u : 0u);
;     const unsigned ngrp = G < 8u ? G : 8u;
;     __builtin_amdgcn_fence(__ATOMIC_RELEASE, "agent");
;     asm volatile("s_waitcnt vmcnt(0)" ::: "memory");
;     const unsigned old = __hip_atomic_fetch_add(bar + 64 * (1 + grp), 1u, __ATOMIC_RELAXED, __HIP_MEMORY_SCOPE_AGENT);
.LBB0_535:
	s_or_b64 exec, exec, s[0:1]
	s_cmp_lt_i32 s95, 4
	s_cbranch_scc1 .LBB0_549
	s_waitcnt vmcnt(0)
	v_sub_u32_e32 v0, 0, v76
	v_cmp_eq_u32_e32 vcc, s21, v0
	s_barrier
	s_and_saveexec_b64 s[0:1], vcc
	s_cbranch_execz .LBB0_548
	s_add_u32 s6, s92, 0x1fe00000
	s_mov_b64 s[4:5], exec
	s_addc_u32 s7, s93, 0
	s_and_b32 s10, s96, 7
	s_nop 0
	s_waitcnt vmcnt(0)
	s_waitcnt vmcnt(0)
	s_lshl_b32 s2, s10, 8
	v_mbcnt_lo_u32_b32 v0, s4, 0
	s_add_u32 s2, s6, s2
	v_mbcnt_hi_u32_b32 v0, s5, v0
	s_addc_u32 s3, s7, 0
	v_cmp_eq_u32_e32 vcc, 0, v0
	s_and_saveexec_b64 s[8:9], vcc
	s_cbranch_execz .LBB0_539
	s_bcnt1_i32_b64 s4, s[4:5]
	v_mov_b32_e32 v1, 0
	v_mov_b32_e32 v2, s4
	global_atomic_add v1, v1, v2, s[2:3] offset:256 sc0

; DI void grid_barrier(const Ctx& c, unsigned idx) {
;     ...
;   asm volatile("s_waitcnt vmcnt(0)" ::: "memory");
;   __syncthreads();
;   if (TIDX == 0) {
;     unsigned* bar = (unsigned*)(p.ws + OFF_BAR);
;     const unsigned G = gridDim.x, grp = blockIdx.x & 7u;
;     const unsigned gsz = (G >> 3) + ((grp < (G & 7u)) ? 1u : 0u);
;     const unsigned ngrp = G < 8u ? G : 8u;
;     __builtin_amdgcn_fence(__ATOMIC_RELEASE, "agent");
;     asm volatile("s_waitcnt vmcnt(0)" ::: "memory");
;     const unsigned old = __hip_atomic_fetch_add(bar + 64 * (1 + grp), 1u, __ATOMIC_RELAXED, __HIP_MEMORY_SCOPE_AGENT);
.LBB0_586:
	s_cmp_lt_u32 s95, 5
	s_cbranch_scc1 .LBB0_600
	s_waitcnt vmcnt(0)
	v_sub_u32_e32 v0, 0, v136
	v_cmp_eq_u32_e32 vcc, s14, v0
	s_waitcnt lgkmcnt(0)
	s_barrier
	s_and_saveexec_b64 s[0:1], vcc
	s_cbranch_execz .LBB0_599
	s_add_u32 s6, s92, 0x1fe00000
	s_mov_b64 s[4:5], exec
	s_addc_u32 s7, s93, 0
	s_and_b32 s10, s96, 7
	s_nop 0
	s_waitcnt vmcnt(0)
	s_waitcnt vmcnt(0)
	s_lshl_b32 s2, s10, 8
	v_mbcnt_lo_u32_b32 v0, s4, 0
	s_add_u32 s2, s6, s2
	v_mbcnt_hi_u32_b32 v0, s5, v0
	s_addc_u32 s3, s7, 0
	v_cmp_eq_u32_e32 vcc, 0, v0
	s_and_saveexec_b64 s[8:9], vcc
	s_cbranch_execz .LBB0_590
	s_bcnt1_i32_b64 s4, s[4:5]
	v_mov_b32_e32 v1, 0
	v_mov_b32_e32 v2, s4
	global_atomic_add v1, v1, v2, s[2:3] offset:256 sc0

; DI void grid_barrier(const Ctx& c, unsigned idx) {
;     ...
;   asm volatile("s_waitcnt vmcnt(0)" ::: "memory");
;   __syncthreads();
;   if (TIDX == 0) {
;     unsigned* bar = (unsigned*)(p.ws + OFF_BAR);
;     const unsigned G = gridDim.x, grp = blockIdx.x & 7u;
;     const unsigned gsz = (G >> 3) + ((grp < (G & 7u)) ? 1u : 0u);
;     const unsigned ngrp = G < 8u ? G : 8u;
;     __builtin_amdgcn_fence(__ATOMIC_RELEASE, "agent");
;     asm volatile("s_waitcnt vmcnt(0)" ::: "memory");
;     const unsigned old = __hip_atomic_fetch_add(bar + 64 * (1 + grp), 1u, __ATOMIC_RELAXED, __HIP_MEMORY_SCOPE_AGENT);
.LBB0_813:
	s_waitcnt lgkmcnt(0)
	s_cmp_lt_i32 s95, 6
	s_cbranch_scc1 .LBB0_827
	s_waitcnt vmcnt(0)
	v_mbcnt_hi_u32_b32 v0, -1, v194
	s_and_b32 s0, s72, 0xffffffc0
	v_sub_u32_e32 v0, 0, v0
	v_cmp_eq_u32_e32 vcc, s0, v0
	s_barrier
	s_and_saveexec_b64 s[0:1], vcc
	s_cbranch_execz .LBB0_826
	s_add_u32 s6, s92, 0x1fe00000
	s_mov_b64 s[4:5], exec
	s_addc_u32 s7, s93, 0
	s_and_b32 s10, s96, 7
	s_nop 0
	s_waitcnt vmcnt(0)
	s_waitcnt vmcnt(0)
	s_lshl_b32 s2, s10, 8
	v_mbcnt_lo_u32_b32 v0, s4, 0
	s_add_u32 s2, s6, s2
	v_mbcnt_hi_u32_b32 v0, s5, v0
	s_addc_u32 s3, s7, 0
	v_cmp_eq_u32_e32 vcc, 0, v0
	s_and_saveexec_b64 s[8:9], vcc
	s_cbranch_execz .LBB0_817
	s_bcnt1_i32_b64 s4, s[4:5]
	v_mov_b32_e32 v1, 0
	v_mov_b32_e32 v2, s4
	global_atomic_add v1, v1, v2, s[2:3] offset:256 sc0

; DI void grid_barrier(const Ctx& c, unsigned idx) {
;     ...
;   asm volatile("s_waitcnt vmcnt(0)" ::: "memory");
;   __syncthreads();
;   if (TIDX == 0) {
;     unsigned* bar = (unsigned*)(p.ws + OFF_BAR);
;     const unsigned G = gridDim.x, grp = blockIdx.x & 7u;
;     const unsigned gsz = (G >> 3) + ((grp < (G & 7u)) ? 1u : 0u);
;     const unsigned ngrp = G < 8u ? G : 8u;
;     __builtin_amdgcn_fence(__ATOMIC_RELEASE, "agent");
;     asm volatile("s_waitcnt vmcnt(0)" ::: "memory");
;     const unsigned old = __hip_atomic_fetch_add(bar + 64 * (1 + grp), 1u, __ATOMIC_RELAXED, __HIP_MEMORY_SCOPE_AGENT);
.LBB0_841:
	s_or_b64 exec, exec, s[0:1]
	s_cmp_lt_i32 s95, 7
	s_cbranch_scc1 .LBB0_855
	s_waitcnt vmcnt(0)
	v_sub_u32_e32 v0, 0, v81
	v_cmp_eq_u32_e32 vcc, s11, v0
	s_waitcnt lgkmcnt(0)
	s_barrier
	s_and_saveexec_b64 s[0:1], vcc
	s_cbranch_execz .LBB0_854
	s_add_u32 s6, s92, 0x1fe00000
	s_mov_b64 s[4:5], exec
	s_addc_u32 s7, s93, 0
	s_and_b32 s10, s96, 7
	s_nop 0
	s_waitcnt vmcnt(0)
	s_waitcnt vmcnt(0)
	s_lshl_b32 s2, s10, 8
	v_mbcnt_lo_u32_b32 v0, s4, 0
	s_add_u32 s2, s6, s2
	v_mbcnt_hi_u32_b32 v0, s5, v0
	s_addc_u32 s3, s7, 0
	v_cmp_eq_u32_e32 vcc, 0, v0
	s_and_saveexec_b64 s[8:9], vcc
	s_cbranch_execz .LBB0_845
	s_bcnt1_i32_b64 s4, s[4:5]
	v_mov_b32_e32 v1, 0
	v_mov_b32_e32 v2, s4
	global_atomic_add v1, v1, v2, s[2:3] offset:256 sc0

; DI void grid_barrier(const Ctx& c, unsigned idx) {
;     ...
;   asm volatile("s_waitcnt vmcnt(0)" ::: "memory");
;   __syncthreads();
;   if (TIDX == 0) {
;     unsigned* bar = (unsigned*)(p.ws + OFF_BAR);
;     const unsigned G = gridDim.x, grp = blockIdx.x & 7u;
;     const unsigned gsz = (G >> 3) + ((grp < (G & 7u)) ? 1u : 0u);
;     const unsigned ngrp = G < 8u ? G : 8u;
;     __builtin_amdgcn_fence(__ATOMIC_RELEASE, "agent");
;     asm volatile("s_waitcnt vmcnt(0)" ::: "memory");
;     const unsigned old = __hip_atomic_fetch_add(bar + 64 * (1 + grp), 1u, __ATOMIC_RELAXED, __HIP_MEMORY_SCOPE_AGENT);
.LBB0_869:
	s_cmp_lt_i32 s95, 8
	s_cbranch_scc1 .LBB0_883
	s_waitcnt vmcnt(0)
	v_sub_u32_e32 v0, 0, v195
	v_cmp_eq_u32_e32 vcc, s8, v0
	s_barrier
	s_and_saveexec_b64 s[0:1], vcc
	s_cbranch_execz .LBB0_882
	s_add_u32 s6, s92, 0x1fe00000
	s_mov_b64 s[4:5], exec
	s_addc_u32 s7, s93, 0
	s_and_b32 s11, s96, 7
	s_nop 0
	s_waitcnt vmcnt(0)
	s_waitcnt vmcnt(0)
	s_lshl_b32 s2, s11, 8
	v_mbcnt_lo_u32_b32 v0, s4, 0
	s_add_u32 s2, s6, s2
	v_mbcnt_hi_u32_b32 v0, s5, v0
	s_addc_u32 s3, s7, 0
	v_cmp_eq_u32_e32 vcc, 0, v0
	s_and_saveexec_b64 s[8:9], vcc
	s_cbranch_execz .LBB0_873
	s_bcnt1_i32_b64 s4, s[4:5]
	v_mov_b32_e32 v1, 0
	v_mov_b32_e32 v2, s4
	global_atomic_add v1, v1, v2, s[2:3] offset:256 sc0

; DI void grid_barrier(const Ctx& c, unsigned idx) {
;     ...
;   asm volatile("s_waitcnt vmcnt(0)" ::: "memory");
;   __syncthreads();
;   if (TIDX == 0) {
;     unsigned* bar = (unsigned*)(p.ws + OFF_BAR);
;     const unsigned G = gridDim.x, grp = blockIdx.x & 7u;
;     const unsigned gsz = (G >> 3) + ((grp < (G & 7u)) ? 1u : 0u);
;     const unsigned ngrp = G < 8u ? G : 8u;
;     __builtin_amdgcn_fence(__ATOMIC_RELEASE, "agent");
;     asm volatile("s_waitcnt vmcnt(0)" ::: "memory");
;     const unsigned old = __hip_atomic_fetch_add(bar + 64 * (1 + grp), 1u, __ATOMIC_RELAXED, __HIP_MEMORY_SCOPE_AGENT);
.LBB0_887:
	s_cmp_lt_u32 s95, 9
	s_cbranch_scc1 .LBB0_901
	s_waitcnt vmcnt(0)
	s_and_b32 s0, s72, 0xffffffc0
	v_sub_u32_e32 v0, 0, v35
	v_cmp_eq_u32_e32 vcc, s0, v0
	s_waitcnt lgkmcnt(0)
	s_barrier
	s_and_saveexec_b64 s[0:1], vcc
	s_cbranch_execz .LBB0_900
	s_add_u32 s4, s92, 0x1fe00000
	s_load_dword s12, s[74:75], 0x180
	s_mov_b64 s[6:7], exec
	s_addc_u32 s5, s93, 0
	s_and_b32 s10, s96, 7
	s_nop 0
	s_waitcnt vmcnt(0) lgkmcnt(0)
	s_waitcnt vmcnt(0)
	s_lshl_b32 s2, s10, 8
	v_mbcnt_lo_u32_b32 v0, s6, 0
	s_add_u32 s2, s4, s2
	v_mbcnt_hi_u32_b32 v0, s7, v0
	s_addc_u32 s3, s5, 0
	v_cmp_eq_u32_e32 vcc, 0, v0
	s_and_saveexec_b64 s[8:9], vcc
	s_cbranch_execz .LBB0_891
	s_bcnt1_i32_b64 s6, s[6:7]
	v_mov_b32_e32 v1, 0
	v_mov_b32_e32 v2, s6
	global_atomic_add v1, v1, v2, s[2:3] offset:256 sc0

; DI void grid_barrier(const Ctx& c, unsigned idx) {
;     ...
;   asm volatile("s_waitcnt vmcnt(0)" ::: "memory");
;   __syncthreads();
;   if (TIDX == 0) {
;     unsigned* bar = (unsigned*)(p.ws + OFF_BAR);
;     const unsigned G = gridDim.x, grp = blockIdx.x & 7u;
;     const unsigned gsz = (G >> 3) + ((grp < (G & 7u)) ? 1u : 0u);
;     const unsigned ngrp = G < 8u ? G : 8u;
;     __builtin_amdgcn_fence(__ATOMIC_RELEASE, "agent");
;     asm volatile("s_waitcnt vmcnt(0)" ::: "memory");
;     const unsigned old = __hip_atomic_fetch_add(bar + 64 * (1 + grp), 1u, __ATOMIC_RELAXED, __HIP_MEMORY_SCOPE_AGENT);
.LBB0_915:
	s_cmp_lt_i32 s95, 10
	s_cbranch_scc1 .LBB0_929
	s_waitcnt vmcnt(0)
	v_sub_u32_e32 v0, 0, v195
	v_cmp_eq_u32_e32 vcc, s16, v0
	s_barrier
	s_and_saveexec_b64 s[0:1], vcc
	s_cbranch_execz .LBB0_928
	s_add_u32 s6, s92, 0x1fe00000
	s_mov_b64 s[4:5], exec
	s_addc_u32 s7, s93, 0
	s_and_b32 s10, s96, 7
	s_nop 0
	s_waitcnt vmcnt(0)
	s_waitcnt vmcnt(0)
	s_lshl_b32 s2, s10, 8
	v_mbcnt_lo_u32_b32 v0, s4, 0
	s_add_u32 s2, s6, s2
	v_mbcnt_hi_u32_b32 v0, s5, v0
	s_addc_u32 s3, s7, 0
	v_cmp_eq_u32_e32 vcc, 0, v0
	s_and_saveexec_b64 s[8:9], vcc
	s_cbranch_execz .LBB0_919
	s_bcnt1_i32_b64 s4, s[4:5]
	v_mov_b32_e32 v1, 0
	v_mov_b32_e32 v2, s4
	global_atomic_add v1, v1, v2, s[2:3] offset:256 sc0

; DI void grid_barrier(const Ctx& c, unsigned idx) {
;     ...
;   asm volatile("s_waitcnt vmcnt(0)" ::: "memory");
;   __syncthreads();
;   if (TIDX == 0) {
;     unsigned* bar = (unsigned*)(p.ws + OFF_BAR);
;     const unsigned G = gridDim.x, grp = blockIdx.x & 7u;
;     const unsigned gsz = (G >> 3) + ((grp < (G & 7u)) ? 1u : 0u);
;     const unsigned ngrp = G < 8u ? G : 8u;
;     __builtin_amdgcn_fence(__ATOMIC_RELEASE, "agent");
;     asm volatile("s_waitcnt vmcnt(0)" ::: "memory");
;     const unsigned old = __hip_atomic_fetch_add(bar + 64 * (1 + grp), 1u, __ATOMIC_RELAXED, __HIP_MEMORY_SCOPE_AGENT);
.LBB0_943:
	s_cmp_lt_i32 s95, 11
	s_cbranch_scc1 .LBB0_957
	s_waitcnt vmcnt(0)
	v_sub_u32_e32 v0, 0, v195
	v_cmp_eq_u32_e32 vcc, s14, v0
	s_barrier
	s_and_saveexec_b64 s[0:1], vcc
	s_cbranch_execz .LBB0_956
	s_add_u32 s6, s92, 0x1fe00000
	s_mov_b64 s[4:5], exec
	s_addc_u32 s7, s93, 0
	s_and_b32 s10, s96, 7
	s_nop 0
	s_waitcnt vmcnt(0)
	s_waitcnt vmcnt(0)
	s_lshl_b32 s2, s10, 8
	v_mbcnt_lo_u32_b32 v0, s4, 0
	s_add_u32 s2, s6, s2
	v_mbcnt_hi_u32_b32 v0, s5, v0
	s_addc_u32 s3, s7, 0
	v_cmp_eq_u32_e32 vcc, 0, v0
	s_and_saveexec_b64 s[8:9], vcc
	s_cbranch_execz .LBB0_947
	s_bcnt1_i32_b64 s4, s[4:5]
	v_mov_b32_e32 v1, 0
	v_mov_b32_e32 v2, s4
	global_atomic_add v1, v1, v2, s[2:3] offset:256 sc0

; DI void grid_barrier(const Ctx& c, unsigned idx) {
;     ...
;   asm volatile("s_waitcnt vmcnt(0)" ::: "memory");
;   __syncthreads();
;   if (TIDX == 0) {
;     unsigned* bar = (unsigned*)(p.ws + OFF_BAR);
;     const unsigned G = gridDim.x, grp = blockIdx.x & 7u;
;     const unsigned gsz = (G >> 3) + ((grp < (G & 7u)) ? 1u : 0u);
;     const unsigned ngrp = G < 8u ? G : 8u;
;     __builtin_amdgcn_fence(__ATOMIC_RELEASE, "agent");
;     asm volatile("s_waitcnt vmcnt(0)" ::: "memory");
;     const unsigned old = __hip_atomic_fetch_add(bar + 64 * (1 + grp), 1u, __ATOMIC_RELAXED, __HIP_MEMORY_SCOPE_AGENT);
.LBB0_961:
	s_cmp_lt_u32 s95, 12
	s_cbranch_scc1 .LBB0_975
	s_waitcnt vmcnt(0)
	s_and_b32 s0, s72, 0xffffffc0
	v_sub_u32_e32 v0, 0, v35
	v_cmp_eq_u32_e32 vcc, s0, v0
	s_waitcnt lgkmcnt(0)
	s_barrier
	s_and_saveexec_b64 s[0:1], vcc
	s_cbranch_execz .LBB0_974
	s_add_u32 s4, s92, 0x1fe00000
	s_load_dword s12, s[74:75], 0x180
	s_mov_b64 s[6:7], exec
	s_addc_u32 s5, s93, 0
	s_and_b32 s10, s96, 7
	s_nop 0
	s_waitcnt vmcnt(0) lgkmcnt(0)
	s_waitcnt vmcnt(0)
	s_lshl_b32 s2, s10, 8
	v_mbcnt_lo_u32_b32 v0, s6, 0
	s_add_u32 s2, s4, s2
	v_mbcnt_hi_u32_b32 v0, s7, v0
	s_addc_u32 s3, s5, 0
	v_cmp_eq_u32_e32 vcc, 0, v0
	s_and_saveexec_b64 s[8:9], vcc
	s_cbranch_execz .LBB0_965
	s_bcnt1_i32_b64 s6, s[6:7]
	v_mov_b32_e32 v1, 0
	v_mov_b32_e32 v2, s6
	global_atomic_add v1, v1, v2, s[2:3] offset:256 sc0

; DI void grid_barrier(const Ctx& c, unsigned idx) {
;     ...
;   asm volatile("s_waitcnt vmcnt(0)" ::: "memory");
;   __syncthreads();
;   if (TIDX == 0) {
;     unsigned* bar = (unsigned*)(p.ws + OFF_BAR);
;     const unsigned G = gridDim.x, grp = blockIdx.x & 7u;
;     const unsigned gsz = (G >> 3) + ((grp < (G & 7u)) ? 1u : 0u);
;     const unsigned ngrp = G < 8u ? G : 8u;
;     __builtin_amdgcn_fence(__ATOMIC_RELEASE, "agent");
;     asm volatile("s_waitcnt vmcnt(0)" ::: "memory");
;     const unsigned old = __hip_atomic_fetch_add(bar + 64 * (1 + grp), 1u, __ATOMIC_RELAXED, __HIP_MEMORY_SCOPE_AGENT);
.LBB0_1245:
	s_cmp_lt_i32 s95, 13
	s_cbranch_scc1 .LBB0_1259
	s_waitcnt vmcnt(0)
	v_sub_u32_e32 v0, 0, v195
	v_cmp_eq_u32_e32 vcc, s36, v0
	s_barrier
	s_and_saveexec_b64 s[0:1], vcc
	s_cbranch_execz .LBB0_1258
	s_add_u32 s6, s92, 0x1fe00000
	s_mov_b64 s[4:5], exec
	s_addc_u32 s7, s93, 0
	s_and_b32 s10, s96, 7
	s_nop 0
	s_waitcnt vmcnt(0)
	s_waitcnt vmcnt(0)
	s_lshl_b32 s2, s10, 8
	v_mbcnt_lo_u32_b32 v0, s4, 0
	s_add_u32 s2, s6, s2
	v_mbcnt_hi_u32_b32 v0, s5, v0
	s_addc_u32 s3, s7, 0
	v_cmp_eq_u32_e32 vcc, 0, v0
	s_and_saveexec_b64 s[8:9], vcc
	s_cbranch_execz .LBB0_1249
	s_bcnt1_i32_b64 s4, s[4:5]
	v_mov_b32_e32 v1, 0
	v_mov_b32_e32 v2, s4
	global_atomic_add v1, v1, v2, s[2:3] offset:256 sc0

; DI void grid_barrier(const Ctx& c, unsigned idx) {
;     ...
;   asm volatile("s_waitcnt vmcnt(0)" ::: "memory");
;   __syncthreads();
;   if (TIDX == 0) {
;     unsigned* bar = (unsigned*)(p.ws + OFF_BAR);
;     const unsigned G = gridDim.x, grp = blockIdx.x & 7u;
;     const unsigned gsz = (G >> 3) + ((grp < (G & 7u)) ? 1u : 0u);
;     const unsigned ngrp = G < 8u ? G : 8u;
;     __builtin_amdgcn_fence(__ATOMIC_RELEASE, "agent");
;     asm volatile("s_waitcnt vmcnt(0)" ::: "memory");
;     const unsigned old = __hip_atomic_fetch_add(bar + 64 * (1 + grp), 1u, __ATOMIC_RELAXED, __HIP_MEMORY_SCOPE_AGENT);
.LBB0_1710:
	s_cmp_lt_i32 s95, 14
	s_cbranch_scc1 .LBB0_1724
	s_waitcnt vmcnt(0)
	v_mbcnt_hi_u32_b32 v0, -1, v194
	s_and_b32 s0, s72, 0xffffffc0
	v_sub_u32_e32 v0, 0, v0
	v_cmp_eq_u32_e32 vcc, s0, v0
	s_barrier
	s_and_saveexec_b64 s[0:1], vcc
	s_cbranch_execz .LBB0_1723
	s_add_u32 s6, s92, 0x1fe00000
	s_mov_b64 s[4:5], exec
	s_addc_u32 s7, s93, 0
	s_and_b32 s10, s96, 7
	s_nop 0
	s_waitcnt vmcnt(0)
	s_waitcnt vmcnt(0)
	s_lshl_b32 s2, s10, 8
	v_mbcnt_lo_u32_b32 v0, s4, 0
	s_add_u32 s2, s6, s2
	v_mbcnt_hi_u32_b32 v0, s5, v0
	s_addc_u32 s3, s7, 0
	v_cmp_eq_u32_e32 vcc, 0, v0
	s_and_saveexec_b64 s[8:9], vcc
	s_cbranch_execz .LBB0_1714
	s_bcnt1_i32_b64 s4, s[4:5]
	v_mov_b32_e32 v1, 0
	v_mov_b32_e32 v2, s4
	global_atomic_add v1, v1, v2, s[2:3] offset:256 sc0

; DI void grid_barrier(const Ctx& c, unsigned idx) {
;     ...
;   asm volatile("s_waitcnt vmcnt(0)" ::: "memory");
;   __syncthreads();
;   if (TIDX == 0) {
;     unsigned* bar = (unsigned*)(p.ws + OFF_BAR);
;     const unsigned G = gridDim.x, grp = blockIdx.x & 7u;
;     const unsigned gsz = (G >> 3) + ((grp < (G & 7u)) ? 1u : 0u);
;     const unsigned ngrp = G < 8u ? G : 8u;
;     __builtin_amdgcn_fence(__ATOMIC_RELEASE, "agent");
;     asm volatile("s_waitcnt vmcnt(0)" ::: "memory");
;     const unsigned old = __hip_atomic_fetch_add(bar + 64 * (1 + grp), 1u, __ATOMIC_RELAXED, __HIP_MEMORY_SCOPE_AGENT);
.LBB0_1802:
	s_or_b64 exec, exec, s[0:1]
	s_cmp_lt_i32 s95, 15
	s_cbranch_scc1 .LBB0_1816
	s_waitcnt vmcnt(0)
	v_sub_u32_e32 v0, 0, v81
	v_cmp_eq_u32_e32 vcc, s16, v0
	s_waitcnt lgkmcnt(0)
	s_barrier
	s_and_saveexec_b64 s[0:1], vcc
	s_cbranch_execz .LBB0_1815
	s_add_u32 s6, s92, 0x1fe00000
	s_mov_b64 s[4:5], exec
	s_addc_u32 s7, s93, 0
	s_and_b32 s10, s96, 7
	s_nop 0
	s_waitcnt vmcnt(0)
	s_waitcnt vmcnt(0)
	s_lshl_b32 s2, s10, 8
	v_mbcnt_lo_u32_b32 v0, s4, 0
	s_add_u32 s2, s6, s2
	v_mbcnt_hi_u32_b32 v0, s5, v0
	s_addc_u32 s3, s7, 0
	v_cmp_eq_u32_e32 vcc, 0, v0
	s_and_saveexec_b64 s[8:9], vcc
	s_cbranch_execz .LBB0_1806
	s_bcnt1_i32_b64 s4, s[4:5]
	v_mov_b32_e32 v1, 0
	v_mov_b32_e32 v2, s4
	global_atomic_add v1, v1, v2, s[2:3] offset:256 sc0

; DI void grid_barrier(const Ctx& c, unsigned idx) {
;     ...
;   asm volatile("s_waitcnt vmcnt(0)" ::: "memory");
;   __syncthreads();
;   if (TIDX == 0) {
;     unsigned* bar = (unsigned*)(p.ws + OFF_BAR);
;     const unsigned G = gridDim.x, grp = blockIdx.x & 7u;
;     const unsigned gsz = (G >> 3) + ((grp < (G & 7u)) ? 1u : 0u);
;     const unsigned ngrp = G < 8u ? G : 8u;
;     __builtin_amdgcn_fence(__ATOMIC_RELEASE, "agent");
;     asm volatile("s_waitcnt vmcnt(0)" ::: "memory");
;     const unsigned old = __hip_atomic_fetch_add(bar + 64 * (1 + grp), 1u, __ATOMIC_RELAXED, __HIP_MEMORY_SCOPE_AGENT);
.LBB0_1830:
	s_cmp_lt_i32 s95, 16
	s_cbranch_scc1 .LBB0_1844
	s_waitcnt vmcnt(0)
	v_sub_u32_e32 v0, 0, v195
	v_cmp_eq_u32_e32 vcc, s16, v0
	s_barrier
	s_and_saveexec_b64 s[0:1], vcc
	s_cbranch_execz .LBB0_1843
	s_add_u32 s6, s92, 0x1fe00000
	s_mov_b64 s[4:5], exec
	s_addc_u32 s7, s93, 0
	s_and_b32 s10, s96, 7
	s_nop 0
	s_waitcnt vmcnt(0)
	s_waitcnt vmcnt(0)
	s_lshl_b32 s2, s10, 8
	v_mbcnt_lo_u32_b32 v0, s4, 0
	s_add_u32 s2, s6, s2
	v_mbcnt_hi_u32_b32 v0, s5, v0
	s_addc_u32 s3, s7, 0
	v_cmp_eq_u32_e32 vcc, 0, v0
	s_and_saveexec_b64 s[8:9], vcc
	s_cbranch_execz .LBB0_1834
	s_bcnt1_i32_b64 s4, s[4:5]
	v_mov_b32_e32 v1, 0
	v_mov_b32_e32 v2, s4
	global_atomic_add v1, v1, v2, s[2:3] offset:256 sc0

; DI void grid_barrier(const Ctx& c, unsigned idx) {
;     ...
;   asm volatile("s_waitcnt vmcnt(0)" ::: "memory");
;   __syncthreads();
;   if (TIDX == 0) {
;     unsigned* bar = (unsigned*)(p.ws + OFF_BAR);
;     const unsigned G = gridDim.x, grp = blockIdx.x & 7u;
;     const unsigned gsz = (G >> 3) + ((grp < (G & 7u)) ? 1u : 0u);
;     const unsigned ngrp = G < 8u ? G : 8u;
;     __builtin_amdgcn_fence(__ATOMIC_RELEASE, "agent");
;     asm volatile("s_waitcnt vmcnt(0)" ::: "memory");
;     const unsigned old = __hip_atomic_fetch_add(bar + 64 * (1 + grp), 1u, __ATOMIC_RELAXED, __HIP_MEMORY_SCOPE_AGENT);
.LBB0_1858:
	s_cmp_lt_i32 s95, 17
	s_cbranch_scc1 .LBB0_1872
	s_waitcnt vmcnt(0)
	v_sub_u32_e32 v0, 0, v195
	v_cmp_eq_u32_e32 vcc, s8, v0
	s_barrier
	s_and_saveexec_b64 s[0:1], vcc
	s_cbranch_execz .LBB0_1871
	s_add_u32 s6, s92, 0x1fe00000
	s_mov_b64 s[4:5], exec
	s_addc_u32 s7, s93, 0
	s_and_b32 s11, s96, 7
	s_nop 0
	s_waitcnt vmcnt(0)
	s_waitcnt vmcnt(0)
	s_lshl_b32 s2, s11, 8
	v_mbcnt_lo_u32_b32 v0, s4, 0
	s_add_u32 s2, s6, s2
	v_mbcnt_hi_u32_b32 v0, s5, v0
	s_addc_u32 s3, s7, 0
	v_cmp_eq_u32_e32 vcc, 0, v0
	s_and_saveexec_b64 s[8:9], vcc
	s_cbranch_execz .LBB0_1862
	s_bcnt1_i32_b64 s4, s[4:5]
	v_mov_b32_e32 v1, 0
	v_mov_b32_e32 v2, s4
	global_atomic_add v1, v1, v2, s[2:3] offset:256 sc0

; DI void grid_barrier(const Ctx& c, unsigned idx) {
;     ...
;   asm volatile("s_waitcnt vmcnt(0)" ::: "memory");
;   __syncthreads();
;   if (TIDX == 0) {
;     unsigned* bar = (unsigned*)(p.ws + OFF_BAR);
;     const unsigned G = gridDim.x, grp = blockIdx.x & 7u;
;     const unsigned gsz = (G >> 3) + ((grp < (G & 7u)) ? 1u : 0u);
;     const unsigned ngrp = G < 8u ? G : 8u;
;     __builtin_amdgcn_fence(__ATOMIC_RELEASE, "agent");
;     asm volatile("s_waitcnt vmcnt(0)" ::: "memory");
;     const unsigned old = __hip_atomic_fetch_add(bar + 64 * (1 + grp), 1u, __ATOMIC_RELAXED, __HIP_MEMORY_SCOPE_AGENT);
.LBB0_1876:
	s_cmp_lt_u32 s95, 18
	s_cbranch_scc1 .LBB0_1890
	s_waitcnt vmcnt(0)
	s_and_b32 s0, s72, 0xffffffc0
	v_sub_u32_e32 v0, 0, v35
	v_cmp_eq_u32_e32 vcc, s0, v0
	s_waitcnt lgkmcnt(0)
	s_barrier
	s_and_saveexec_b64 s[0:1], vcc
	s_cbranch_execz .LBB0_1889
	s_add_u32 s4, s92, 0x1fe00000
	s_load_dword s12, s[74:75], 0x180
	s_mov_b64 s[6:7], exec
	s_addc_u32 s5, s93, 0
	s_and_b32 s10, s96, 7
	s_nop 0
	s_waitcnt vmcnt(0) lgkmcnt(0)
	s_waitcnt vmcnt(0)
	s_lshl_b32 s2, s10, 8
	v_mbcnt_lo_u32_b32 v0, s6, 0
	s_add_u32 s2, s4, s2
	v_mbcnt_hi_u32_b32 v0, s7, v0
	s_addc_u32 s3, s5, 0
	v_cmp_eq_u32_e32 vcc, 0, v0
	s_and_saveexec_b64 s[8:9], vcc
	s_cbranch_execz .LBB0_1880
	s_bcnt1_i32_b64 s6, s[6:7]
	v_mov_b32_e32 v1, 0
	v_mov_b32_e32 v2, s6
	global_atomic_add v1, v1, v2, s[2:3] offset:256 sc0

; DI void grid_barrier(const Ctx& c, unsigned idx) {
;     ...
;   asm volatile("s_waitcnt vmcnt(0)" ::: "memory");
;   __syncthreads();
;   if (TIDX == 0) {
;     unsigned* bar = (unsigned*)(p.ws + OFF_BAR);
;     const unsigned G = gridDim.x, grp = blockIdx.x & 7u;
;     const unsigned gsz = (G >> 3) + ((grp < (G & 7u)) ? 1u : 0u);
;     const unsigned ngrp = G < 8u ? G : 8u;
;     __builtin_amdgcn_fence(__ATOMIC_RELEASE, "agent");
;     asm volatile("s_waitcnt vmcnt(0)" ::: "memory");
;     const unsigned old = __hip_atomic_fetch_add(bar + 64 * (1 + grp), 1u, __ATOMIC_RELAXED, __HIP_MEMORY_SCOPE_AGENT);
.LBB0_1904:
	s_cmp_lt_i32 s95, 19
	s_cbranch_scc1 .LBB0_1918
	s_waitcnt vmcnt(0)
	v_sub_u32_e32 v0, 0, v195
	v_cmp_eq_u32_e32 vcc, s16, v0
	s_barrier
	s_and_saveexec_b64 s[0:1], vcc
	s_cbranch_execz .LBB0_1917
	s_add_u32 s6, s92, 0x1fe00000
	s_mov_b64 s[4:5], exec
	s_addc_u32 s7, s93, 0
	s_and_b32 s10, s96, 7
	s_nop 0
	s_waitcnt vmcnt(0)
	s_waitcnt vmcnt(0)
	s_lshl_b32 s2, s10, 8
	v_mbcnt_lo_u32_b32 v0, s4, 0
	s_add_u32 s2, s6, s2
	v_mbcnt_hi_u32_b32 v0, s5, v0
	s_addc_u32 s3, s7, 0
	v_cmp_eq_u32_e32 vcc, 0, v0
	s_and_saveexec_b64 s[8:9], vcc
	s_cbranch_execz .LBB0_1908
	s_bcnt1_i32_b64 s4, s[4:5]
	v_mov_b32_e32 v1, 0
	v_mov_b32_e32 v2, s4
	global_atomic_add v1, v1, v2, s[2:3] offset:256 sc0

; DI void grid_barrier(const Ctx& c, unsigned idx) {
;     ...
;   asm volatile("s_waitcnt vmcnt(0)" ::: "memory");
;   __syncthreads();
;   if (TIDX == 0) {
;     unsigned* bar = (unsigned*)(p.ws + OFF_BAR);
;     const unsigned G = gridDim.x, grp = blockIdx.x & 7u;
;     const unsigned gsz = (G >> 3) + ((grp < (G & 7u)) ? 1u : 0u);
;     const unsigned ngrp = G < 8u ? G : 8u;
;     __builtin_amdgcn_fence(__ATOMIC_RELEASE, "agent");
;     asm volatile("s_waitcnt vmcnt(0)" ::: "memory");
;     const unsigned old = __hip_atomic_fetch_add(bar + 64 * (1 + grp), 1u, __ATOMIC_RELAXED, __HIP_MEMORY_SCOPE_AGENT);
.LBB0_1932:
	s_cmp_lt_i32 s95, 20
	s_cbranch_scc1 .LBB0_1946
	s_waitcnt vmcnt(0)
	v_sub_u32_e32 v0, 0, v195
	v_cmp_eq_u32_e32 vcc, s14, v0
	s_barrier
	s_and_saveexec_b64 s[0:1], vcc
	s_cbranch_execz .LBB0_1945
	s_add_u32 s6, s92, 0x1fe00000
	s_mov_b64 s[4:5], exec
	s_addc_u32 s7, s93, 0
	s_and_b32 s10, s96, 7
	s_nop 0
	s_waitcnt vmcnt(0)
	s_waitcnt vmcnt(0)
	s_lshl_b32 s2, s10, 8
	v_mbcnt_lo_u32_b32 v0, s4, 0
	s_add_u32 s2, s6, s2
	v_mbcnt_hi_u32_b32 v0, s5, v0
	s_addc_u32 s3, s7, 0
	v_cmp_eq_u32_e32 vcc, 0, v0
	s_and_saveexec_b64 s[8:9], vcc
	s_cbranch_execz .LBB0_1936
	s_bcnt1_i32_b64 s4, s[4:5]
	v_mov_b32_e32 v1, 0
	v_mov_b32_e32 v2, s4
	global_atomic_add v1, v1, v2, s[2:3] offset:256 sc0

; DI void grid_barrier(const Ctx& c, unsigned idx) {
;     ...
;   asm volatile("s_waitcnt vmcnt(0)" ::: "memory");
;   __syncthreads();
;   if (TIDX == 0) {
;     unsigned* bar = (unsigned*)(p.ws + OFF_BAR);
;     const unsigned G = gridDim.x, grp = blockIdx.x & 7u;
;     const unsigned gsz = (G >> 3) + ((grp < (G & 7u)) ? 1u : 0u);
;     const unsigned ngrp = G < 8u ? G : 8u;
;     __builtin_amdgcn_fence(__ATOMIC_RELEASE, "agent");
;     asm volatile("s_waitcnt vmcnt(0)" ::: "memory");
;     const unsigned old = __hip_atomic_fetch_add(bar + 64 * (1 + grp), 1u, __ATOMIC_RELAXED, __HIP_MEMORY_SCOPE_AGENT);
.LBB0_1950:
	s_cmp_lt_u32 s95, 21
	s_cbranch_scc1 .LBB0_1964
	s_waitcnt vmcnt(0)
	s_and_b32 s0, s72, 0xffffffc0
	v_sub_u32_e32 v0, 0, v21
	v_cmp_eq_u32_e32 vcc, s0, v0
	s_waitcnt lgkmcnt(0)
	s_barrier
	s_and_saveexec_b64 s[0:1], vcc
	s_cbranch_execz .LBB0_1963
	s_add_u32 s4, s92, 0x1fe00000
	s_load_dword s12, s[74:75], 0x180
	s_mov_b64 s[6:7], exec
	s_addc_u32 s5, s93, 0
	s_and_b32 s10, s96, 7
	s_nop 0
	s_waitcnt vmcnt(0) lgkmcnt(0)
	s_waitcnt vmcnt(0)
	s_lshl_b32 s2, s10, 8
	v_mbcnt_lo_u32_b32 v0, s6, 0
	s_add_u32 s2, s4, s2
	v_mbcnt_hi_u32_b32 v0, s7, v0
	s_addc_u32 s3, s5, 0
	v_cmp_eq_u32_e32 vcc, 0, v0
	s_and_saveexec_b64 s[8:9], vcc
	s_cbranch_execz .LBB0_1954
	s_bcnt1_i32_b64 s6, s[6:7]
	v_mov_b32_e32 v1, 0
	v_mov_b32_e32 v2, s6
	global_atomic_add v1, v1, v2, s[2:3] offset:256 sc0
